# v35 + gate unit: counted wait for the first load group only (W_g / bias / u loads stay in flight during the LayerNorm)
# speedup vs baseline: 1.0026x; 1.0026x over previous
; #define LAS __attribute__((address_space(3)))
; #define GASP __attribute__((address_space(1)))
; __device__ __forceinline__ void gate_unit(const Params& p, LAS unsigned char* L, int row0, int n, int g, int sample_b) {
;     ...
;     const int nks = active ? min((tb + 1) * 2, n / 16) : 0;
;     const int t = tid >> 2, ch = tid & 3; const bool ldr = t < n;
;     f32x4 xv[8], sp[4];
;     if (ldr) { const float* src = GVF + (size_t)(row0 + t) * 512 + g * 128 + ch * 32; const GASP f32x4* sq = (const GASP f32x4*)(GST + (size_t)(row0 + t) * 16);
; #pragma unroll
;         for (int i = 0; i < 8; ++i) xv[i] = *(const GASP f32x4*)(src + 4 * i);
; #pragma unroll
;         for (int i = 0; i < 4; ++i) sp[i] = sq[i]; }
;     bf16x8 wf[8];
;     { const bf16_t* wp = WSB + (size_t)(g * 128 + tb * 32 + r) * 128 + 8 * hi;
; #pragma unroll
;       for (int ks = 0; ks < 8; ++ks) if (ks < nks) wf[ks] = *(const GASP bf16x8*)(wp + ks * 16); }
;     const int te = tb * 32 + r;
;     u32x2 uu[8]; float bias = 0.f;
;     if (active) { const bf16_t* up = UB + (size_t)(row0 + te) * 512 + g * 128 + dh * 64 + 4 * hi; bias = bs[g * 128 + te];
; #pragma unroll
;         for (int i = 0; i < 8; ++i) uu[i] = *(const GASP u32x2*)(up + (i >> 2) * 32 + 8 * (i & 3)); }
;     if (ldr) {
;         float s = 0.f, q = 0.f;
; #pragma unroll
;         for (int i = 0; i < 4; ++i) { s += sp[i][0] + sp[i][2]; q += sp[i][1] + sp[i][3]; }
;         const float mean = s * (1.f / 512.f), rstd = 1.f / sqrtf(q * (1.f / 512.f) - mean * mean + LN_EPS);
;         const float* gp = lng + g * 128 + ch * 32; const float* bp = lnb + g * 128 + ch * 32;
; #pragma unroll
;         for (int i = 0; i < 4; ++i) {
;             const f32x4 ya = (xv[2 * i] - mean) * rstd * *(const GASP f32x4*)(gp + 8 * i) + *(const GASP f32x4*)(bp + 8 * i);
;             const f32x4 yc = (xv[2 * i + 1] - mean) * rstd * *(const GASP f32x4*)(gp + 8 * i + 4) + *(const GASP f32x4*)(bp + 8 * i + 4);
;             u32x4 w; w.x = pk2(ya[0], ya[1]); w.y = pk2(ya[2], ya[3]); w.z = pk2(yc[0], yc[1]); w.w = pk2(yc[2], yc[3]);
;             *(LAS u32x4*)(L + t * DA_VRS + ch * 64 + i * 16) = w;
;             if (sample_b >= 0) { float* o = p.out + OUT_GV + (size_t)(sample_b * 32 + t) * 512 + g * 128 + ch * 32 + 8 * i; *(GASP f32x4*)o = ya; *(GASP f32x4*)(o + 4) = yc; }
;         }
;     }
.LBB0_906:
	v_or_b32_e32 v82, s28, v82
	v_or_b32_e32 v106, s14, v82
	s_ashr_i32 s5, s15, 8
	v_lshlrev_b32_e32 v84, 10, v106
	v_mov_b32_e32 v85, v1
	v_lshl_add_u64 v[84:85], s[60:61], 0, v[84:85]
	s_lshl_b32 s84, s5, 6
	v_lshl_add_u64 v[84:85], v[0:1], 1, v[84:85]
	s_ashr_i32 s85, s84, 31
	v_readlane_b32 s14, v252, 8
	v_lshlrev_b32_e32 v100, 3, v83
	v_lshl_add_u64 v[84:85], s[84:85], 1, v[84:85]
	v_mov_b32_e32 v101, v1
	v_or_b32_e32 v86, v0, v82
	v_mov_b32_e32 v87, v1
	v_readlane_b32 s15, v252, 9
	v_lshl_add_u64 v[84:85], v[84:85], 0, v[100:101]
	s_nop 0
	v_lshl_add_u64 v[86:87], v[86:87], 2, s[14:15]
	global_load_dword v82, v[86:87], off
	global_load_dwordx2 v[98:99], v[84:85], off
	global_load_dwordx2 v[96:97], v[84:85], off offset:16
	global_load_dwordx2 v[94:95], v[84:85], off offset:32
	global_load_dwordx2 v[92:93], v[84:85], off offset:48
	global_load_dwordx2 v[90:91], v[84:85], off offset:64
	global_load_dwordx2 v[88:89], v[84:85], off offset:80
	global_load_dwordx2 v[86:87], v[84:85], off offset:96
	s_nop 0
	global_load_dwordx2 v[84:85], v[84:85], off offset:112
	s_cmp_eq_u32 s28, 0
	s_cbranch_scc1 .Lgw_11
	s_cmp_eq_u32 s28, 32
	s_cbranch_scc1 .Lgw_13
	s_cmp_eq_u32 s28, 64
	s_cbranch_scc1 .Lgw_15
	s_waitcnt vmcnt(17)
	s_branch .Lgw_done
.Lgw_15:
	s_waitcnt vmcnt(15)
	s_branch .Lgw_done
.Lgw_13:
	s_waitcnt vmcnt(13)
	s_branch .Lgw_done
.Lgw_11:
	s_waitcnt vmcnt(11)
.Lgw_done:
	s_and_saveexec_b64 s[86:87], s[12:13]
	s_cbranch_execz .LBB0_908
	v_pk_add_f32 v[78:79], v[78:79], v[80:81]
	v_pk_add_f32 v[74:75], v[74:75], v[76:77]
	v_pk_add_f32 v[78:79], v[78:79], 0 op_sel_hi:[1,0]
	v_pk_add_f32 v[70:71], v[70:71], v[72:73]
	v_pk_add_f32 v[74:75], v[74:75], v[78:79]
	v_pk_add_f32 v[66:67], v[66:67], v[68:69]
	v_pk_add_f32 v[70:71], v[70:71], v[74:75]
	s_mov_b32 s12, 0x3b000000
	v_pk_add_f32 v[66:67], v[66:67], v[70:71]
	v_mov_b32_e32 v103, v1
	v_pk_mul_f32 v[78:79], v[66:67], s[12:13] op_sel_hi:[1,0]
	s_nop 0
	v_fma_f32 v66, -v78, v78, v79
	v_add_f32_e32 v66, 0x3727c5ac, v66
	v_cmp_gt_f32_e32 vcc, s35, v66
	v_mul_f32_e32 v67, 0x4f800000, v66
	v_sub_f32_e32 v65, v65, v78
	v_cndmask_b32_e32 v66, v66, v67, vcc
	v_sqrt_f32_e32 v67, v66
	v_sub_f32_e32 v64, v64, v78
	v_sub_f32_e32 v63, v63, v78
	v_sub_f32_e32 v62, v62, v78
	v_add_u32_e32 v68, -1, v67
	v_fma_f32 v69, -v68, v67, v66
	v_cmp_ge_f32_e64 s[12:13], 0, v69
	v_add_u32_e32 v69, 1, v67
	v_sub_f32_e32 v33, v33, v78
	v_cndmask_b32_e64 v68, v67, v68, s[12:13]
	v_fma_f32 v67, -v69, v67, v66
	v_cmp_lt_f32_e64 s[12:13], 0, v67
	v_sub_f32_e32 v32, v32, v78
	v_sub_f32_e32 v31, v31, v78
	v_cndmask_b32_e64 v67, v68, v69, s[12:13]
	v_mul_f32_e32 v68, 0x37800000, v67
	v_cndmask_b32_e32 v67, v67, v68, vcc
	v_cmp_class_f32_e32 vcc, v66, v170
	v_sub_f32_e32 v30, v30, v78
	v_sub_f32_e32 v25, v25, v78
	v_cndmask_b32_e32 v66, v67, v66, vcc
	v_div_scale_f32 v67, s[12:13], v66, v66, 1.0
	v_rcp_f32_e32 v68, v67
	v_readlane_b32 s12, v252, 10
	v_readlane_b32 s13, v252, 11
	v_sub_f32_e32 v24, v24, v78
	v_fma_f32 v69, -v67, v68, 1.0
	v_fmac_f32_e32 v68, v69, v68
	v_div_scale_f32 v69, vcc, 1.0, v66, 1.0
	v_mul_f32_e32 v70, v69, v68
	v_fma_f32 v71, -v67, v70, v69
	v_fmac_f32_e32 v70, v71, v68
	v_fma_f32 v67, -v67, v70, v69
	v_div_fmas_f32 v67, v67, v68, v70
	v_lshlrev_b64 v[68:69], 2, v[0:1]
	v_div_fixup_f32 v80, v67, v66, 1.0
	v_lshl_add_u64 v[66:67], s[18:19], 0, v[68:69]
	v_lshl_add_u64 v[68:69], s[12:13], 0, v[68:69]
	v_lshl_add_u64 v[66:67], v[66:67], 0, v[102:103]
	v_lshl_add_u64 v[74:75], v[68:69], 0, v[102:103]
	v_mul_lo_u32 v68, v104, s88
	v_lshlrev_b32_e32 v69, 6, v105
	v_add3_u32 v79, 0, v68, v69
	v_pk_mul_f32 v[72:73], v[62:63], v[80:81] op_sel_hi:[1,0]
	v_pk_mul_f32 v[76:77], v[64:65], v[80:81] op_sel_hi:[1,0]
	v_pk_mul_f32 v[30:31], v[30:31], v[80:81] op_sel_hi:[1,0]
	v_pk_mul_f32 v[32:33], v[32:33], v[80:81] op_sel_hi:[1,0]
	v_sub_f32_e32 v23, v23, v78
	v_sub_f32_e32 v22, v22, v78
	v_sub_f32_e32 v21, v21, v78
	v_sub_f32_e32 v20, v20, v78
	v_sub_f32_e32 v19, v19, v78
	v_sub_f32_e32 v18, v18, v78
	v_pk_mul_f32 v[22:23], v[22:23], v[80:81] op_sel_hi:[1,0]
	v_pk_mul_f32 v[24:25], v[24:25], v[80:81] op_sel_hi:[1,0]
	v_pk_mul_f32 v[18:19], v[18:19], v[80:81] op_sel_hi:[1,0]
	v_pk_mul_f32 v[20:21], v[20:21], v[80:81] op_sel_hi:[1,0]
	v_sub_f32_e32 v13, v13, v78
	v_sub_f32_e32 v12, v12, v78
	v_sub_f32_e32 v11, v11, v78
	v_sub_f32_e32 v10, v10, v78
	v_pk_mul_f32 v[10:11], v[10:11], v[80:81] op_sel_hi:[1,0]
	v_pk_mul_f32 v[12:13], v[12:13], v[80:81] op_sel_hi:[1,0]
	v_sub_f32_e32 v9, v9, v78
	v_sub_f32_e32 v8, v8, v78
	v_sub_f32_e32 v7, v7, v78
	v_sub_f32_e32 v6, v6, v78
	v_sub_f32_e32 v5, v5, v78
	v_sub_f32_e32 v4, v4, v78
	v_sub_f32_e32 v3, v3, v78
	v_sub_f32_e32 v2, v2, v78
	v_pk_mul_f32 v[6:7], v[6:7], v[80:81] op_sel_hi:[1,0]
	v_pk_mul_f32 v[8:9], v[8:9], v[80:81] op_sel_hi:[1,0]
	v_pk_mul_f32 v[2:3], v[2:3], v[80:81] op_sel_hi:[1,0]
	v_pk_mul_f32 v[4:5], v[4:5], v[80:81] op_sel_hi:[1,0]
	v_pk_fma_f32 v[24:25], v[24:25], v[138:139], v[186:187]
	v_pk_fma_f32 v[104:105], v[32:33], v[134:135], v[182:183]
	v_pk_fma_f32 v[76:77], v[76:77], v[130:131], v[178:179]
	v_pk_fma_f32 v[72:73], v[72:73], v[128:129], v[176:177]
	v_pk_fma_f32 v[32:33], v[30:31], v[132:133], v[180:181]
	v_cvt_pk_bf16_f32 v30, v72, v73
	v_cvt_pk_bf16_f32 v31, v76, v77
	v_cvt_pk_bf16_f32 v32, v32, v33
	v_cvt_pk_bf16_f32 v33, v104, v105
	ds_write_b128 v79, v[30:33]
	v_pk_fma_f32 v[22:23], v[22:23], v[136:137], v[184:185]
	v_pk_fma_f32 v[30:31], v[20:21], v[142:143], v[190:191]
	v_pk_fma_f32 v[20:21], v[18:19], v[140:141], v[188:189]
	v_cvt_pk_bf16_f32 v18, v22, v23
	v_cvt_pk_bf16_f32 v19, v24, v25
	v_cvt_pk_bf16_f32 v20, v20, v21
	v_cvt_pk_bf16_f32 v21, v30, v31
	ds_write_b128 v79, v[18:21] offset:16
	v_sub_f32_e32 v19, v29, v78
	v_sub_f32_e32 v18, v28, v78
	v_sub_f32_e32 v21, v27, v78
	v_sub_f32_e32 v20, v26, v78
	v_pk_mul_f32 v[102:103], v[20:21], v[80:81] op_sel_hi:[1,0]
	v_pk_mul_f32 v[104:105], v[18:19], v[80:81] op_sel_hi:[1,0]
	s_nop 0
	s_nop 0
	v_pk_fma_f32 v[8:9], v[8:9], v[154:155], v[202:203]
	v_pk_fma_f32 v[64:65], v[12:13], v[150:151], v[198:199]
	v_pk_fma_f32 v[72:73], v[104:105], v[146:147], v[194:195]
	v_pk_fma_f32 v[70:71], v[102:103], v[144:145], v[192:193]
	v_pk_fma_f32 v[12:13], v[10:11], v[148:149], v[196:197]
	v_cvt_pk_bf16_f32 v10, v70, v71
	v_cvt_pk_bf16_f32 v11, v72, v73
	v_cvt_pk_bf16_f32 v12, v12, v13
	v_cvt_pk_bf16_f32 v13, v64, v65
	ds_write_b128 v79, v[10:13] offset:32
	v_pk_fma_f32 v[6:7], v[6:7], v[152:153], v[200:201]
	v_pk_fma_f32 v[10:11], v[4:5], v[158:159], v[206:207]
	v_pk_fma_f32 v[4:5], v[2:3], v[156:157], v[204:205]
	v_cvt_pk_bf16_f32 v2, v6, v7
	v_cvt_pk_bf16_f32 v3, v8, v9
	v_cvt_pk_bf16_f32 v4, v4, v5
	v_cvt_pk_bf16_f32 v5, v10, v11
	ds_write_b128 v79, v[2:5] offset:48
